# LayerNorm row loops: per-row gain/bias/shift/scale loads issued together with counted waits (no full drains behind stores)
# speedup vs baseline: 1.0154x; 1.0086x over previous
; DI void ln_rows(const Params& p, const float* g, const float* bb, int nrows, int mod_layer, int sh_chunk, bool write_act) {
;     ...
; #pragma unroll
;     for (int rr = 0; rr < 2; ++rr) {
;       if (rr == 1 && !has1) break;
;       const int row = rr ? row1 : row0;
;       const float rstd = rr ? rb : ra;
;       float* dst = xrow(p, row);
;       if (write_act && lane == 0) ((float2*)(p.ws + O_ST))[row] = make_float2(rr ? mb : ma, rstd);
;       const float* m = (const float*)(p.ws + O_MOD) + (size_t)mod_layer * 17 * 6144 + rowb(row) * 6144 + sh_chunk * 1024;
; #pragma unroll
;       for (int i = 0; i < 4; ++i) {
;         int col = (i * 64 + lane) * 4;
;         float4 v = rr ? vb[i] : va[i];
;         float4 gg = *(const float4*)(g + col);
;         float4 bv = *(const float4*)(bb + col);
;         float4 y;
;         y.x = v.x * rstd * gg.x + bv.x; y.y = v.y * rstd * gg.y + bv.y;
;         y.z = v.z * rstd * gg.z + bv.z; y.w = v.w * rstd * gg.w + bv.w;
;         if (!write_act) *(float4*)(dst + col) = y;
;         if (write_act) {
;           float4 sh = *(const float4*)(m + col);
;           float4 sc = *(const float4*)(m + 1024 + col);
;           uint2 o;
;           o.x = pack2(y.x * (1.f + sc.x) + sh.x, y.y * (1.f + sc.y) + sh.y);
;           o.y = pack2(y.z * (1.f + sc.z) + sh.z, y.w * (1.f + sc.w) + sh.w);
;           *(uint2*)(act + (size_t)row * AP + col) = o;
;         }
;       }
.LBB0_809:
	s_or_b64 exec, exec, s[2:3]
	v_min_i32_e32 v14, 0x10000, v81
	v_ashrrev_i32_e32 v14, 12, v14
	v_mul_i32_i24_e32 v14, 0x1800, v14
	v_ashrrev_i32_e32 v15, 31, v14
	v_lshl_add_u64 v[14:15], v[14:15], 2, s[10:11]
	s_mov_b64 s[2:3], 0x1000
	v_lshl_add_u64 v[16:17], v[14:15], 0, s[2:3]
	v_pk_mul_f32 v[18:19], v[56:57], v[20:21] op_sel_hi:[1,0]
	v_lshl_add_u64 v[14:15], v[14:15], 0, v[0:1]
	v_lshl_add_u64 v[56:57], v[16:17], 0, v[0:1]
	v_pk_mul_f32 v[60:61], v[58:59], v[20:21] op_sel_hi:[1,0]
	v_mov_b64_e32 v[154:155], v[56:57]
	global_load_dwordx4 v[90:93], v[36:37], off
	global_load_dwordx4 v[106:109], v[38:39], off
	global_load_dwordx4 v[122:125], v[14:15], off
	global_load_dwordx4 v[138:141], v[154:155], off
	global_load_dwordx4 v[94:97], v[36:37], off offset:1024
	global_load_dwordx4 v[110:113], v[38:39], off offset:1024
	global_load_dwordx4 v[126:129], v[14:15], off offset:1024
	global_load_dwordx4 v[142:145], v[154:155], off offset:1024
	global_load_dwordx4 v[98:101], v[36:37], off offset:2048
	global_load_dwordx4 v[114:117], v[38:39], off offset:2048
	global_load_dwordx4 v[130:133], v[14:15], off offset:2048
	global_load_dwordx4 v[146:149], v[154:155], off offset:2048
	global_load_dwordx4 v[102:105], v[36:37], off offset:3072
	global_load_dwordx4 v[118:121], v[38:39], off offset:3072
	global_load_dwordx4 v[134:137], v[14:15], off offset:3072
	global_load_dwordx4 v[150:153], v[154:155], off offset:3072
	s_waitcnt vmcnt(12)
	v_mov_b64_e32 v[22:23], v[90:91]
	v_mov_b64_e32 v[24:25], v[92:93]
	v_mov_b64_e32 v[26:27], v[106:107]
	v_mov_b64_e32 v[28:29], v[108:109]
	v_mov_b64_e32 v[30:31], v[122:123]
	v_mov_b64_e32 v[32:33], v[124:125]
	s_nop 0
	v_mov_b64_e32 v[56:57], v[138:139]
	v_mov_b64_e32 v[58:59], v[140:141]
	s_mov_b32 s2, 0x50cc000
	v_mov_b32_e32 v51, v1
	v_mov_b32_e32 v53, v1
	v_mov_b32_e32 v55, v1
	v_pk_fma_f32 v[18:19], v[18:19], v[22:23], v[26:27]
	v_pk_add_f32 v[22:23], v[56:57], 1.0 op_sel_hi:[1,0]
	v_pk_mul_f32 v[26:27], v[10:11], v[20:21] op_sel_hi:[1,0]
	v_pk_fma_f32 v[18:19], v[18:19], v[22:23], v[30:31]
	v_pk_mul_f32 v[56:57], v[12:13], v[20:21] op_sel_hi:[1,0]
	v_cvt_pk_bf16_f32 v22, v18, v19
	v_pk_fma_f32 v[18:19], v[60:61], v[24:25], v[28:29]
	v_pk_add_f32 v[24:25], v[58:59], 1.0 op_sel_hi:[1,0]
	v_lshl_add_u64 v[30:31], v[16:17], 0, v[50:51]
	v_pk_fma_f32 v[18:19], v[18:19], v[24:25], v[32:33]
	s_nop 0
	v_cvt_pk_bf16_f32 v23, v18, v19
	v_lshl_add_u64 v[18:19], s[84:85], 0, v[48:49]
	v_add_co_u32_e32 v18, vcc, s2, v18
	s_nop 1
	v_addc_co_u32_e32 v19, vcc, 0, v19, vcc
	global_store_dwordx2 v[18:19], v[22:23], off offset:256
	s_waitcnt vmcnt(9)
	v_mov_b64_e32 v[10:11], v[94:95]
	v_mov_b64_e32 v[12:13], v[96:97]
	s_nop 0
	v_mov_b64_e32 v[22:23], v[110:111]
	v_mov_b64_e32 v[24:25], v[112:113]
	v_pk_fma_f32 v[10:11], v[26:27], v[10:11], v[22:23]
	v_mov_b64_e32 v[26:27], v[126:127]
	v_mov_b64_e32 v[28:29], v[128:129]
	s_nop 0
	v_mov_b64_e32 v[30:31], v[142:143]
	v_mov_b64_e32 v[32:33], v[144:145]
	v_pk_fma_f32 v[12:13], v[56:57], v[12:13], v[24:25]
	v_pk_add_f32 v[22:23], v[30:31], 1.0 op_sel_hi:[1,0]
	s_nop 0
	v_pk_fma_f32 v[10:11], v[10:11], v[22:23], v[26:27]
	v_pk_add_f32 v[22:23], v[32:33], 1.0 op_sel_hi:[1,0]
	v_cvt_pk_bf16_f32 v10, v10, v11
	v_pk_fma_f32 v[12:13], v[12:13], v[22:23], v[28:29]
	v_pk_mul_f32 v[22:23], v[6:7], v[20:21] op_sel_hi:[1,0]
	v_cvt_pk_bf16_f32 v11, v12, v13
	global_store_dwordx2 v[18:19], v[10:11], off offset:768
	v_pk_mul_f32 v[30:31], v[8:9], v[20:21] op_sel_hi:[1,0]
	s_waitcnt vmcnt(6)
	v_mov_b64_e32 v[6:7], v[98:99]
	v_mov_b64_e32 v[8:9], v[100:101]
	v_mov_b64_e32 v[10:11], v[114:115]
	v_mov_b64_e32 v[12:13], v[116:117]
	v_lshl_add_u64 v[26:27], v[16:17], 0, v[52:53]
	v_lshl_add_u64 v[16:17], v[16:17], 0, v[54:55]
	v_pk_fma_f32 v[6:7], v[22:23], v[6:7], v[10:11]
	v_mov_b64_e32 v[22:23], v[130:131]
	v_mov_b64_e32 v[24:25], v[132:133]
	s_nop 0
	v_mov_b64_e32 v[26:27], v[146:147]
	v_mov_b64_e32 v[28:29], v[148:149]
	v_pk_fma_f32 v[8:9], v[30:31], v[8:9], v[12:13]
	v_pk_add_f32 v[10:11], v[26:27], 1.0 op_sel_hi:[1,0]
	s_nop 0
	v_pk_fma_f32 v[6:7], v[6:7], v[10:11], v[22:23]
	v_pk_add_f32 v[10:11], v[28:29], 1.0 op_sel_hi:[1,0]
	v_cvt_pk_bf16_f32 v6, v6, v7
	v_pk_fma_f32 v[8:9], v[8:9], v[10:11], v[24:25]
	v_pk_mul_f32 v[10:11], v[2:3], v[20:21] op_sel_hi:[1,0]
	v_cvt_pk_bf16_f32 v7, v8, v9
	global_store_dwordx2 v[18:19], v[6:7], off offset:1280
	v_pk_mul_f32 v[20:21], v[4:5], v[20:21] op_sel_hi:[1,0]
	s_waitcnt vmcnt(3)
	v_mov_b64_e32 v[2:3], v[102:103]
	v_mov_b64_e32 v[4:5], v[104:105]
	v_mov_b64_e32 v[6:7], v[118:119]
	v_mov_b64_e32 v[8:9], v[120:121]
	v_pk_fma_f32 v[2:3], v[10:11], v[2:3], v[6:7]
	v_mov_b64_e32 v[10:11], v[134:135]
	v_mov_b64_e32 v[12:13], v[136:137]
	s_nop 0
	v_mov_b64_e32 v[14:15], v[150:151]
	v_mov_b64_e32 v[16:17], v[152:153]
	v_pk_fma_f32 v[4:5], v[20:21], v[4:5], v[8:9]
	v_pk_add_f32 v[6:7], v[14:15], 1.0 op_sel_hi:[1,0]
	s_nop 0
	v_pk_fma_f32 v[2:3], v[2:3], v[6:7], v[10:11]
	v_pk_add_f32 v[6:7], v[16:17], 1.0 op_sel_hi:[1,0]
	v_cvt_pk_bf16_f32 v2, v2, v3
	v_pk_fma_f32 v[4:5], v[4:5], v[6:7], v[12:13]
	s_nop 0
	v_cvt_pk_bf16_f32 v3, v4, v5
	global_store_dwordx2 v[18:19], v[2:3], off offset:1792

; DI void ln_rows(const Params& p, const float* g, const float* bb, int nrows, int mod_layer, int sh_chunk, bool write_act) {
;     ...
;       const float* m = (const float*)(p.ws + O_MOD) + (size_t)mod_layer * 17 * 6144 + rowb(row) * 6144 + sh_chunk * 1024;
; #pragma unroll
;       for (int i = 0; i < 4; ++i) {
;         int col = (i * 64 + lane) * 4;
;         float4 v = rr ? vb[i] : va[i];
;         float4 gg = *(const float4*)(g + col);
;         float4 bv = *(const float4*)(bb + col);
;         float4 y;
;         y.x = v.x * rstd * gg.x + bv.x; y.y = v.y * rstd * gg.y + bv.y;
;         y.z = v.z * rstd * gg.z + bv.z; y.w = v.w * rstd * gg.w + bv.w;
;         if (!write_act) *(float4*)(dst + col) = y;
;         if (write_act) {
;           float4 sh = *(const float4*)(m + col);
;           float4 sc = *(const float4*)(m + 1024 + col);
;           uint2 o;
;           o.x = pack2(y.x * (1.f + sc.x) + sh.x, y.y * (1.f + sc.y) + sh.y);
;           o.y = pack2(y.z * (1.f + sc.z) + sh.z, y.w * (1.f + sc.w) + sh.w);
;           *(uint2*)(act + (size_t)row * AP + col) = o;
;         }
.LBB0_821:
	s_or_b64 exec, exec, s[16:17]
	v_min_i32_e32 v15, 0x10000, v80
	v_ashrrev_i32_e32 v15, 12, v15
	v_mul_i32_i24_e32 v16, 0x1800, v15
	v_ashrrev_i32_e32 v17, 31, v16
	v_lshl_add_u64 v[16:17], v[16:17], 2, s[10:11]
	s_mov_b64 s[16:17], 0x1000
	v_lshl_add_u64 v[22:23], v[16:17], 0, s[16:17]
	v_lshl_add_u64 v[16:17], v[16:17], 0, v[0:1]
	v_lshl_add_u64 v[86:87], v[22:23], 0, v[0:1]
	v_pk_mul_f32 v[24:25], v[68:69], v[26:27] op_sel_hi:[1,0]
	v_pk_mul_f32 v[72:73], v[70:71], v[26:27] op_sel_hi:[1,0]
	v_mov_b64_e32 v[154:155], v[86:87]
	global_load_dwordx4 v[90:93], v[36:37], off
	global_load_dwordx4 v[106:109], v[38:39], off
	global_load_dwordx4 v[122:125], v[16:17], off
	global_load_dwordx4 v[138:141], v[154:155], off
	global_load_dwordx4 v[94:97], v[36:37], off offset:1024
	global_load_dwordx4 v[110:113], v[38:39], off offset:1024
	global_load_dwordx4 v[126:129], v[16:17], off offset:1024
	global_load_dwordx4 v[142:145], v[154:155], off offset:1024
	global_load_dwordx4 v[98:101], v[36:37], off offset:2048
	global_load_dwordx4 v[114:117], v[38:39], off offset:2048
	global_load_dwordx4 v[130:133], v[16:17], off offset:2048
	global_load_dwordx4 v[146:149], v[154:155], off offset:2048
	global_load_dwordx4 v[102:105], v[36:37], off offset:3072
	global_load_dwordx4 v[118:121], v[38:39], off offset:3072
	global_load_dwordx4 v[134:137], v[16:17], off offset:3072
	global_load_dwordx4 v[150:153], v[154:155], off offset:3072
	s_waitcnt vmcnt(12)
	v_mov_b64_e32 v[30:31], v[90:91]
	v_mov_b64_e32 v[32:33], v[92:93]
	v_mov_b64_e32 v[68:69], v[106:107]
	v_mov_b64_e32 v[70:71], v[108:109]
	v_mov_b64_e32 v[82:83], v[122:123]
	v_mov_b64_e32 v[84:85], v[124:125]
	s_nop 0
	v_mov_b64_e32 v[86:87], v[138:139]
	v_mov_b64_e32 v[88:89], v[140:141]
	s_mov_b32 s16, 0x50cc000
	v_mov_b32_e32 v51, v1
	v_mov_b32_e32 v53, v1
	v_mov_b32_e32 v55, v1
	v_pk_fma_f32 v[24:25], v[24:25], v[30:31], v[68:69]
	v_pk_add_f32 v[30:31], v[86:87], 1.0 op_sel_hi:[1,0]
	v_pk_mul_f32 v[68:69], v[64:65], v[26:27] op_sel_hi:[1,0]
	v_pk_fma_f32 v[24:25], v[24:25], v[30:31], v[82:83]
	v_lshl_add_u64 v[82:83], v[22:23], 0, v[50:51]
	v_cvt_pk_bf16_f32 v30, v24, v25
	v_pk_fma_f32 v[24:25], v[72:73], v[32:33], v[70:71]
	v_pk_add_f32 v[32:33], v[88:89], 1.0 op_sel_hi:[1,0]
	v_pk_mul_f32 v[72:73], v[66:67], v[26:27] op_sel_hi:[1,0]
	v_pk_fma_f32 v[24:25], v[24:25], v[32:33], v[84:85]
	s_nop 0
	v_cvt_pk_bf16_f32 v31, v24, v25
	v_lshl_add_u64 v[24:25], s[84:85], 0, v[42:43]
	v_add_co_u32_e32 v24, vcc, s16, v24
	s_nop 1
	v_addc_co_u32_e32 v25, vcc, 0, v25, vcc
	global_store_dwordx2 v[24:25], v[30:31], off offset:256
	s_waitcnt vmcnt(9)
	v_mov_b64_e32 v[30:31], v[94:95]
	v_mov_b64_e32 v[32:33], v[96:97]
	s_nop 0
	v_mov_b64_e32 v[64:65], v[110:111]
	v_mov_b64_e32 v[66:67], v[112:113]
	v_pk_fma_f32 v[30:31], v[68:69], v[30:31], v[64:65]
	v_mov_b64_e32 v[68:69], v[126:127]
	v_mov_b64_e32 v[70:71], v[128:129]
	s_nop 0
	v_mov_b64_e32 v[82:83], v[142:143]
	v_mov_b64_e32 v[84:85], v[144:145]
	v_pk_fma_f32 v[32:33], v[72:73], v[32:33], v[66:67]
	v_pk_add_f32 v[64:65], v[82:83], 1.0 op_sel_hi:[1,0]
	s_nop 0
	v_pk_fma_f32 v[30:31], v[30:31], v[64:65], v[68:69]
	v_pk_add_f32 v[64:65], v[84:85], 1.0 op_sel_hi:[1,0]
	v_cvt_pk_bf16_f32 v30, v30, v31
	v_pk_fma_f32 v[32:33], v[32:33], v[64:65], v[70:71]
	v_lshl_add_u64 v[70:71], v[22:23], 0, v[52:53]
	v_cvt_pk_bf16_f32 v31, v32, v33
	global_store_dwordx2 v[24:25], v[30:31], off offset:768
	v_pk_mul_f32 v[32:33], v[28:29], v[26:27] op_sel_hi:[1,0]
	v_pk_mul_f32 v[82:83], v[62:63], v[26:27] op_sel_hi:[1,0]
	s_waitcnt vmcnt(6)
	v_mov_b64_e32 v[28:29], v[98:99]
	v_mov_b64_e32 v[30:31], v[100:101]
	v_mov_b64_e32 v[62:63], v[114:115]
	v_mov_b64_e32 v[64:65], v[116:117]
	v_mov_b64_e32 v[66:67], v[130:131]
	v_mov_b64_e32 v[68:69], v[132:133]
	s_nop 0
	v_mov_b64_e32 v[70:71], v[146:147]
	v_mov_b64_e32 v[72:73], v[148:149]
	v_lshl_add_u64 v[22:23], v[22:23], 0, v[54:55]
	v_pk_fma_f32 v[28:29], v[32:33], v[28:29], v[62:63]
	v_pk_add_f32 v[32:33], v[70:71], 1.0 op_sel_hi:[1,0]
	v_pk_fma_f32 v[30:31], v[82:83], v[30:31], v[64:65]
	v_pk_fma_f32 v[28:29], v[28:29], v[32:33], v[66:67]
	v_pk_add_f32 v[32:33], v[72:73], 1.0 op_sel_hi:[1,0]
	v_cvt_pk_bf16_f32 v28, v28, v29
	v_pk_fma_f32 v[30:31], v[30:31], v[32:33], v[68:69]
	v_pk_mul_f32 v[62:63], v[20:21], v[26:27] op_sel_hi:[1,0]
	v_cvt_pk_bf16_f32 v29, v30, v31
	global_store_dwordx2 v[24:25], v[28:29], off offset:1280
	v_pk_mul_f32 v[30:31], v[18:19], v[26:27] op_sel_hi:[1,0]
	s_waitcnt vmcnt(3)
	v_mov_b64_e32 v[18:19], v[102:103]
	v_mov_b64_e32 v[20:21], v[104:105]
	v_mov_b64_e32 v[26:27], v[118:119]
	v_mov_b64_e32 v[28:29], v[120:121]
	v_pk_fma_f32 v[26:27], v[30:31], v[18:19], v[26:27]
	v_mov_b64_e32 v[16:17], v[134:135]
	v_mov_b64_e32 v[18:19], v[136:137]
	s_nop 0
	v_mov_b64_e32 v[30:31], v[150:151]
	v_mov_b64_e32 v[32:33], v[152:153]
	v_pk_fma_f32 v[20:21], v[62:63], v[20:21], v[28:29]
	v_pk_add_f32 v[22:23], v[30:31], 1.0 op_sel_hi:[1,0]
	s_nop 0
	v_pk_fma_f32 v[16:17], v[26:27], v[22:23], v[16:17]
	v_pk_add_f32 v[22:23], v[32:33], 1.0 op_sel_hi:[1,0]
	v_cvt_pk_bf16_f32 v16, v16, v17
	v_pk_fma_f32 v[18:19], v[20:21], v[22:23], v[18:19]
	s_nop 0
	v_cvt_pk_bf16_f32 v17, v18, v19
	global_store_dwordx2 v[24:25], v[16:17], off offset:1792
	s_and_saveexec_b64 s[16:17], s[2:3]
	s_cbranch_execz .LBB0_810
	v_mul_f32_e32 v15, 0x4b800000, v14
	v_cndmask_b32_e64 v14, v14, v15, s[4:5]
	v_rsq_f32_e32 v14, v14
	s_nop 0
	v_mul_f32_e32 v15, 0x45800000, v14
	v_cndmask_b32_e64 v20, v14, v15, s[4:5]
	s_and_saveexec_b64 s[2:3], s[0:1]
	s_cbranch_execz .LBB0_809
	v_lshl_add_u64 v[14:15], s[84:85], 0, v[46:47]
	v_add_co_u32_e32 v14, vcc, 0x3e28c000, v14
	v_mov_b32_e32 v61, v20
	s_nop 0
	v_addc_co_u32_e32 v15, vcc, 0, v15, vcc
	global_store_dwordx2 v[14:15], v[60:61], off offset:256
	s_branch .LBB0_809

; DI void ln_rows(const Params& p, const float* g, const float* bb, int nrows, int mod_layer, int sh_chunk, bool write_act) {
;     ...
;       const float* m = (const float*)(p.ws + O_MOD) + (size_t)mod_layer * 17 * 6144 + rowb(row) * 6144 + sh_chunk * 1024;
; #pragma unroll
;       for (int i = 0; i < 4; ++i) {
;         int col = (i * 64 + lane) * 4;
;         float4 v = rr ? vb[i] : va[i];
;         float4 gg = *(const float4*)(g + col);
;         float4 bv = *(const float4*)(bb + col);
;         float4 y;
;         y.x = v.x * rstd * gg.x + bv.x; y.y = v.y * rstd * gg.y + bv.y;
;         y.z = v.z * rstd * gg.z + bv.z; y.w = v.w * rstd * gg.w + bv.w;
;         if (!write_act) *(float4*)(dst + col) = y;
;         if (write_act) {
;           float4 sh = *(const float4*)(m + col);
;           float4 sc = *(const float4*)(m + 1024 + col);
;           uint2 o;
;           o.x = pack2(y.x * (1.f + sc.x) + sh.x, y.y * (1.f + sc.y) + sh.y);
;           o.y = pack2(y.z * (1.f + sc.z) + sh.z, y.w * (1.f + sc.w) + sh.w);
;           *(uint2*)(act + (size_t)row * AP + col) = o;
;         }
.LBB0_881:
	s_or_b64 exec, exec, s[4:5]
	global_load_dwordx4 v[90:93], v[44:45], off
	global_load_dwordx4 v[106:109], v[46:47], off
	global_load_dwordx4 v[94:97], v[44:45], off offset:1024
	global_load_dwordx4 v[110:113], v[46:47], off offset:1024
	global_load_dwordx4 v[98:101], v[44:45], off offset:2048
	global_load_dwordx4 v[114:117], v[46:47], off offset:2048
	global_load_dwordx4 v[102:105], v[44:45], off offset:3072
	global_load_dwordx4 v[118:121], v[46:47], off offset:3072
	s_and_b64 vcc, exec, s[74:75]
	s_cbranch_vccnz .Lln2_nomod_r0
	v_min_i32_e32 v156, 0x10000, v82
	v_ashrrev_i32_e32 v156, 12, v156
	v_mul_i32_i24_e32 v156, 0x1800, v156
	v_ashrrev_i32_e32 v157, 31, v156
	v_lshl_add_u64 v[156:157], v[156:157], 2, s[10:11]
	v_lshl_add_u64 v[156:157], v[156:157], 0, v[0:1]
	s_mov_b64 s[98:99], 0x1000
	v_lshl_add_u64 v[158:159], v[156:157], 0, s[98:99]
	global_load_dwordx4 v[122:125], v[156:157], off
	global_load_dwordx4 v[138:141], v[158:159], off
	global_load_dwordx4 v[126:129], v[156:157], off offset:1024
	global_load_dwordx4 v[142:145], v[158:159], off offset:1024
	global_load_dwordx4 v[130:133], v[156:157], off offset:2048
	global_load_dwordx4 v[146:149], v[158:159], off offset:2048
	global_load_dwordx4 v[134:137], v[156:157], off offset:3072
	global_load_dwordx4 v[150:153], v[158:159], off offset:3072
.Lln2_nomod_r0:
	s_waitcnt vmcnt(6)
	v_mov_b64_e32 v[30:31], v[90:91]
	v_mov_b64_e32 v[32:33], v[92:93]
	v_mov_b64_e32 v[84:85], v[106:107]
	v_mov_b64_e32 v[86:87], v[108:109]
	v_pk_mul_f32 v[4:5], v[76:77], v[22:23] op_sel_hi:[1,0]
	v_pk_mul_f32 v[16:17], v[2:3], v[22:23] op_sel_hi:[1,0]
	v_cndmask_b32_e64 v2, 0, 1, s[74:75]
	v_cmp_ne_u32_e64 s[4:5], 1, v2
	s_andn2_b64 vcc, exec, s[74:75]
	s_mov_b64 s[16:17], -1
	v_pk_fma_f32 v[2:3], v[4:5], v[30:31], v[84:85]
	v_pk_fma_f32 v[4:5], v[16:17], v[32:33], v[86:87]
	s_cbranch_vccnz .LBB0_883
	s_mov_b64 s[16:17], 0
	global_store_dwordx4 v[60:61], v[2:5], off
.LBB0_883:
	v_min_i32_e32 v15, 0x10000, v82
	v_ashrrev_i32_e32 v15, 12, v15
	v_mul_i32_i24_e32 v16, 0x1800, v15
	v_ashrrev_i32_e32 v17, 31, v16
	v_lshl_add_u64 v[30:31], v[16:17], 2, s[10:11]
	s_mov_b64 s[8:9], 0x1000
	v_lshl_add_u64 v[24:25], v[30:31], 0, s[8:9]
	s_andn2_b64 vcc, exec, s[16:17]
	v_lshl_add_u64 v[16:17], s[84:85], 0, v[50:51]
	s_cbranch_vccnz .LBB0_885
	v_lshl_add_u64 v[32:33], v[30:31], 0, v[0:1]
	v_lshl_add_u64 v[84:85], v[24:25], 0, v[0:1]
	s_waitcnt vmcnt(6)
	v_mov_b64_e32 v[76:77], v[122:123]
	v_mov_b64_e32 v[78:79], v[124:125]
	s_nop 0
	v_mov_b64_e32 v[84:85], v[138:139]
	v_mov_b64_e32 v[86:87], v[140:141]
	v_pk_add_f32 v[32:33], v[84:85], 1.0 op_sel_hi:[1,0]
	s_nop 0
	v_pk_fma_f32 v[2:3], v[2:3], v[32:33], v[76:77]
	v_pk_add_f32 v[32:33], v[86:87], 1.0 op_sel_hi:[1,0]
	v_cvt_pk_bf16_f32 v2, v2, v3
	v_pk_fma_f32 v[4:5], v[4:5], v[32:33], v[78:79]
	s_nop 0
	v_cvt_pk_bf16_f32 v3, v4, v5
	v_add_co_u32_e32 v4, vcc, 0x50cc000, v16
	s_nop 1
	v_addc_co_u32_e32 v5, vcc, 0, v17, vcc
	global_store_dwordx2 v[4:5], v[2:3], off offset:256
.LBB0_885:
	s_waitcnt vmcnt(5)
	v_mov_b64_e32 v[2:3], v[94:95]
	v_mov_b64_e32 v[4:5], v[96:97]
	s_nop 0
	v_mov_b64_e32 v[76:77], v[110:111]
	v_mov_b64_e32 v[78:79], v[112:113]
	v_mov_b32_e32 v23, v22
	v_pk_mul_f32 v[32:33], v[72:73], v[22:23]
	v_pk_mul_f32 v[72:73], v[74:75], v[22:23]
	s_and_b64 vcc, exec, s[4:5]
	s_mov_b64 s[16:17], -1
	v_pk_fma_f32 v[2:3], v[32:33], v[2:3], v[76:77]
	v_pk_fma_f32 v[4:5], v[72:73], v[4:5], v[78:79]
	s_cbranch_vccnz .LBB0_887
	s_mov_b64 s[16:17], 0
	global_store_dwordx4 v[60:61], v[2:5], off offset:1024
.LBB0_887:
	s_andn2_b64 vcc, exec, s[16:17]
	s_cbranch_vccnz .LBB0_889
	v_lshlrev_b32_e32 v72, 2, v38
	v_mov_b32_e32 v73, v1
	v_lshl_add_u64 v[32:33], v[30:31], 0, v[0:1]
	v_lshl_add_u64 v[76:77], v[24:25], 0, v[72:73]
	s_waitcnt vmcnt(5)
	v_mov_b64_e32 v[72:73], v[126:127]
	v_mov_b64_e32 v[74:75], v[128:129]
	s_nop 0
	v_mov_b64_e32 v[76:77], v[142:143]
	v_mov_b64_e32 v[78:79], v[144:145]
	v_pk_add_f32 v[32:33], v[76:77], 1.0 op_sel_hi:[1,0]
	s_nop 0
	v_pk_fma_f32 v[2:3], v[2:3], v[32:33], v[72:73]
	v_pk_add_f32 v[32:33], v[78:79], 1.0 op_sel_hi:[1,0]
	v_cvt_pk_bf16_f32 v2, v2, v3
	v_pk_fma_f32 v[4:5], v[4:5], v[32:33], v[74:75]
	s_nop 0
	v_cvt_pk_bf16_f32 v3, v4, v5
	v_add_co_u32_e32 v4, vcc, 0x50cc000, v16
	s_nop 1
	v_addc_co_u32_e32 v5, vcc, 0, v17, vcc
	global_store_dwordx2 v[4:5], v[2:3], off offset:768
.LBB0_889:
	s_waitcnt vmcnt(4)
	v_mov_b64_e32 v[2:3], v[98:99]
	v_mov_b64_e32 v[4:5], v[100:101]
	s_nop 0
	v_mov_b64_e32 v[72:73], v[114:115]
	v_mov_b64_e32 v[74:75], v[116:117]
	v_pk_mul_f32 v[32:33], v[70:71], v[22:23]
	v_pk_mul_f32 v[68:69], v[68:69], v[22:23]
	s_and_b64 vcc, exec, s[4:5]
	s_mov_b64 s[16:17], -1
	v_pk_fma_f32 v[2:3], v[32:33], v[2:3], v[72:73]
	v_pk_fma_f32 v[4:5], v[68:69], v[4:5], v[74:75]
	s_cbranch_vccnz .LBB0_891
	s_mov_b64 s[16:17], 0
	global_store_dwordx4 v[60:61], v[2:5], off offset:2048
.LBB0_891:
	s_andn2_b64 vcc, exec, s[16:17]
	s_cbranch_vccnz .LBB0_893
	v_lshlrev_b32_e32 v68, 2, v40
	v_mov_b32_e32 v69, v1
	v_lshl_add_u64 v[32:33], v[30:31], 0, v[0:1]
	v_lshl_add_u64 v[72:73], v[24:25], 0, v[68:69]
	s_waitcnt vmcnt(4)
	v_mov_b64_e32 v[68:69], v[130:131]
	v_mov_b64_e32 v[70:71], v[132:133]
	s_nop 0
	v_mov_b64_e32 v[72:73], v[146:147]
	v_mov_b64_e32 v[74:75], v[148:149]
	v_pk_add_f32 v[32:33], v[72:73], 1.0 op_sel_hi:[1,0]
	s_nop 0
	v_pk_fma_f32 v[2:3], v[2:3], v[32:33], v[68:69]
	v_pk_add_f32 v[32:33], v[74:75], 1.0 op_sel_hi:[1,0]
	v_cvt_pk_bf16_f32 v2, v2, v3
	v_pk_fma_f32 v[4:5], v[4:5], v[32:33], v[70:71]
	s_nop 0
	v_cvt_pk_bf16_f32 v3, v4, v5
	v_add_co_u32_e32 v4, vcc, 0x50cc000, v16
	s_nop 1
	v_addc_co_u32_e32 v5, vcc, 0, v17, vcc
	global_store_dwordx2 v[4:5], v[2:3], off offset:1280
.LBB0_893:
	s_waitcnt vmcnt(3)
	v_mov_b64_e32 v[2:3], v[102:103]
	v_mov_b64_e32 v[4:5], v[104:105]
	s_nop 0
	v_mov_b64_e32 v[68:69], v[118:119]
	v_mov_b64_e32 v[70:71], v[120:121]
	v_pk_mul_f32 v[20:21], v[20:21], v[22:23]
	v_pk_mul_f32 v[18:19], v[18:19], v[22:23]
	s_and_b64 vcc, exec, s[4:5]
	s_mov_b64 s[16:17], -1
	v_pk_fma_f32 v[2:3], v[20:21], v[2:3], v[68:69]
	v_pk_fma_f32 v[4:5], v[18:19], v[4:5], v[70:71]
	s_cbranch_vccnz .LBB0_896
	global_store_dwordx4 v[60:61], v[2:5], off offset:3072
	s_cbranch_execz .LBB0_897

; DI void ln_rows(const Params& p, const float* g, const float* bb, int nrows, int mod_layer, int sh_chunk, bool write_act) {
;     ...
;         if (write_act) {
;           float4 sh = *(const float4*)(m + col);
;           float4 sc = *(const float4*)(m + 1024 + col);
;           uint2 o;
;           o.x = pack2(y.x * (1.f + sc.x) + sh.x, y.y * (1.f + sc.y) + sh.y);
;           o.y = pack2(y.z * (1.f + sc.z) + sh.z, y.w * (1.f + sc.w) + sh.w);
;           *(uint2*)(act + (size_t)row * AP + col) = o;
;         }
.LBB0_897:
	v_lshlrev_b32_e32 v20, 2, v42
	v_mov_b32_e32 v21, v1
	v_lshl_add_u64 v[18:19], v[30:31], 0, v[0:1]
	v_lshl_add_u64 v[22:23], v[24:25], 0, v[20:21]
	s_waitcnt vmcnt(3)
	v_mov_b64_e32 v[18:19], v[134:135]
	v_mov_b64_e32 v[20:21], v[136:137]
	s_nop 0
	v_mov_b64_e32 v[22:23], v[150:151]
	v_mov_b64_e32 v[24:25], v[152:153]
	v_pk_add_f32 v[22:23], v[22:23], 1.0 op_sel_hi:[1,0]
	s_nop 0
	v_pk_fma_f32 v[2:3], v[2:3], v[22:23], v[18:19]
	v_pk_add_f32 v[18:19], v[24:25], 1.0 op_sel_hi:[1,0]
	v_cvt_pk_bf16_f32 v2, v2, v3
	v_pk_fma_f32 v[4:5], v[4:5], v[18:19], v[20:21]
	s_nop 0
	v_cvt_pk_bf16_f32 v3, v4, v5
	v_add_co_u32_e32 v4, vcc, 0x50cc000, v16
	s_nop 1
	v_addc_co_u32_e32 v5, vcc, 0, v17, vcc
	global_store_dwordx2 v[4:5], v[2:3], off offset:1792
	s_and_saveexec_b64 s[16:17], s[2:3]
	s_cbranch_execz .LBB0_870

; DI void ln_rows(const Params& p, const float* g, const float* bb, int nrows, int mod_layer, int sh_chunk, bool write_act) {
;     ...
;     for (int rr = 0; rr < 2; ++rr) {
;       if (rr == 1 && !has1) break;
;       const int row = rr ? row1 : row0;
;       const float rstd = rr ? rb : ra;
;       float* dst = xrow(p, row);
;       if (write_act && lane == 0) ((float2*)(p.ws + O_ST))[row] = make_float2(rr ? mb : ma, rstd);
;       const float* m = (const float*)(p.ws + O_MOD) + (size_t)mod_layer * 17 * 6144 + rowb(row) * 6144 + sh_chunk * 1024;
; #pragma unroll
;       for (int i = 0; i < 4; ++i) {
;         int col = (i * 64 + lane) * 4;
;         float4 v = rr ? vb[i] : va[i];
;         float4 gg = *(const float4*)(g + col);
;         float4 bv = *(const float4*)(bb + col);
;         float4 y;
;         y.x = v.x * rstd * gg.x + bv.x; y.y = v.y * rstd * gg.y + bv.y;
;         y.z = v.z * rstd * gg.z + bv.z; y.w = v.w * rstd * gg.w + bv.w;
;         if (!write_act) *(float4*)(dst + col) = y;
;         if (write_act) {
;           float4 sh = *(const float4*)(m + col);
;           float4 sc = *(const float4*)(m + 1024 + col);
;           uint2 o;
;           o.x = pack2(y.x * (1.f + sc.x) + sh.x, y.y * (1.f + sc.y) + sh.y);
;           o.y = pack2(y.z * (1.f + sc.z) + sh.z, y.w * (1.f + sc.w) + sh.w);
;           *(uint2*)(act + (size_t)row * AP + col) = o;
;         }
.LBB0_900:
	s_or_b64 exec, exec, s[2:3]
	global_load_dwordx4 v[90:93], v[44:45], off
	global_load_dwordx4 v[106:109], v[46:47], off
	global_load_dwordx4 v[94:97], v[44:45], off offset:1024
	global_load_dwordx4 v[110:113], v[46:47], off offset:1024
	global_load_dwordx4 v[98:101], v[44:45], off offset:2048
	global_load_dwordx4 v[114:117], v[46:47], off offset:2048
	global_load_dwordx4 v[102:105], v[44:45], off offset:3072
	global_load_dwordx4 v[118:121], v[46:47], off offset:3072
	s_and_b64 vcc, exec, s[74:75]
	s_cbranch_vccnz .Lln2_nomod_r1
	v_min_i32_e32 v156, 0x10000, v83
	v_ashrrev_i32_e32 v156, 12, v156
	v_mul_i32_i24_e32 v156, 0x1800, v156
	v_ashrrev_i32_e32 v157, 31, v156
	v_lshl_add_u64 v[156:157], v[156:157], 2, s[10:11]
	v_lshl_add_u64 v[156:157], v[156:157], 0, v[0:1]
	s_mov_b64 s[98:99], 0x1000
	v_lshl_add_u64 v[158:159], v[156:157], 0, s[98:99]
	global_load_dwordx4 v[122:125], v[156:157], off
	global_load_dwordx4 v[138:141], v[158:159], off
	global_load_dwordx4 v[126:129], v[156:157], off offset:1024
	global_load_dwordx4 v[142:145], v[158:159], off offset:1024
	global_load_dwordx4 v[130:133], v[156:157], off offset:2048
	global_load_dwordx4 v[146:149], v[158:159], off offset:2048
	global_load_dwordx4 v[134:137], v[156:157], off offset:3072
	global_load_dwordx4 v[150:153], v[158:159], off offset:3072
.Lln2_nomod_r1:
	s_waitcnt vmcnt(6)
	v_mov_b64_e32 v[2:3], v[90:91]
	v_mov_b64_e32 v[4:5], v[92:93]
	v_mov_b64_e32 v[18:19], v[106:107]
	v_mov_b64_e32 v[20:21], v[108:109]
	v_pk_mul_f32 v[14:15], v[64:65], v[16:17] op_sel_hi:[1,0]
	v_pk_mul_f32 v[22:23], v[62:63], v[16:17] op_sel_hi:[1,0]
	s_and_b64 vcc, exec, s[4:5]
	s_mov_b64 s[2:3], -1
	v_pk_fma_f32 v[2:3], v[14:15], v[2:3], v[18:19]
	v_pk_fma_f32 v[4:5], v[22:23], v[4:5], v[20:21]
	s_cbranch_vccnz .LBB0_902
	v_lshl_add_u64 v[14:15], v[58:59], 0, v[0:1]
	s_mov_b64 s[2:3], 0
	global_store_dwordx4 v[14:15], v[2:5], off
.LBB0_902:
	v_min_i32_e32 v14, 0x10000, v83
	v_ashrrev_i32_e32 v14, 12, v14
	v_mul_i32_i24_e32 v14, 0x1800, v14
	v_ashrrev_i32_e32 v15, 31, v14
	v_lshl_add_u64 v[20:21], v[14:15], 2, s[10:11]
	s_mov_b64 s[6:7], 0x1000
	v_lshl_add_u64 v[18:19], v[20:21], 0, s[6:7]
	s_andn2_b64 vcc, exec, s[2:3]
	v_lshl_add_u64 v[14:15], s[84:85], 0, v[56:57]
	s_cbranch_vccnz .LBB0_904
	v_lshl_add_u64 v[22:23], v[20:21], 0, v[0:1]
	v_lshl_add_u64 v[30:31], v[18:19], 0, v[0:1]
	s_waitcnt vmcnt(6)
	v_mov_b64_e32 v[22:23], v[122:123]
	v_mov_b64_e32 v[24:25], v[124:125]
	s_nop 0
	v_mov_b64_e32 v[30:31], v[138:139]
	v_mov_b64_e32 v[32:33], v[140:141]
	v_pk_add_f32 v[30:31], v[30:31], 1.0 op_sel_hi:[1,0]
	s_nop 0
	v_pk_fma_f32 v[2:3], v[2:3], v[30:31], v[22:23]
	v_pk_add_f32 v[22:23], v[32:33], 1.0 op_sel_hi:[1,0]
	v_cvt_pk_bf16_f32 v2, v2, v3
	v_pk_fma_f32 v[4:5], v[4:5], v[22:23], v[24:25]
	s_nop 0
	v_cvt_pk_bf16_f32 v3, v4, v5
	v_add_co_u32_e32 v4, vcc, 0x50cc000, v14
	s_nop 1
	v_addc_co_u32_e32 v5, vcc, 0, v15, vcc
	global_store_dwordx2 v[4:5], v[2:3], off offset:256
.LBB0_904:
	s_waitcnt vmcnt(5)
	v_mov_b64_e32 v[2:3], v[94:95]
	v_mov_b64_e32 v[4:5], v[96:97]
	s_nop 0
	v_mov_b64_e32 v[22:23], v[110:111]
	v_mov_b64_e32 v[24:25], v[112:113]
	v_mov_b32_e32 v17, v16
	v_pk_mul_f32 v[26:27], v[26:27], v[16:17]
	v_pk_mul_f32 v[28:29], v[28:29], v[16:17]
	s_and_b64 vcc, exec, s[4:5]
	s_mov_b64 s[2:3], -1
	v_pk_fma_f32 v[2:3], v[26:27], v[2:3], v[22:23]
	v_pk_fma_f32 v[4:5], v[28:29], v[4:5], v[24:25]
	s_cbranch_vccnz .LBB0_906
	v_lshl_add_u64 v[22:23], v[58:59], 0, v[0:1]
	s_mov_b64 s[2:3], 0
	global_store_dwordx4 v[22:23], v[2:5], off offset:1024
; DI void ln_rows(const Params& p, const float* g, const float* bb, int nrows, int mod_layer, int sh_chunk, bool write_act) {
;     ...
;       for (int i = 0; i < 4; ++i) {
;         int col = (i * 64 + lane) * 4;
;         float4 v = rr ? vb[i] : va[i];
;         float4 gg = *(const float4*)(g + col);
;         float4 bv = *(const float4*)(bb + col);
;         float4 y;
;         y.x = v.x * rstd * gg.x + bv.x; y.y = v.y * rstd * gg.y + bv.y;
;         y.z = v.z * rstd * gg.z + bv.z; y.w = v.w * rstd * gg.w + bv.w;
;         if (!write_act) *(float4*)(dst + col) = y;
;         if (write_act) {
;           float4 sh = *(const float4*)(m + col);
;           float4 sc = *(const float4*)(m + 1024 + col);
;           uint2 o;
;           o.x = pack2(y.x * (1.f + sc.x) + sh.x, y.y * (1.f + sc.y) + sh.y);
;           o.y = pack2(y.z * (1.f + sc.z) + sh.z, y.w * (1.f + sc.w) + sh.w);
;           *(uint2*)(act + (size_t)row * AP + col) = o;
;         }
.LBB0_906:
	s_andn2_b64 vcc, exec, s[2:3]
	s_cbranch_vccnz .LBB0_908
	v_lshlrev_b32_e32 v24, 2, v38
	v_mov_b32_e32 v25, v1
	v_lshl_add_u64 v[22:23], v[20:21], 0, v[0:1]
	v_lshl_add_u64 v[26:27], v[18:19], 0, v[24:25]
	s_waitcnt vmcnt(5)
	v_mov_b64_e32 v[22:23], v[126:127]
	v_mov_b64_e32 v[24:25], v[128:129]
	s_nop 0
	v_mov_b64_e32 v[26:27], v[142:143]
	v_mov_b64_e32 v[28:29], v[144:145]
	v_pk_add_f32 v[26:27], v[26:27], 1.0 op_sel_hi:[1,0]
	s_nop 0
	v_pk_fma_f32 v[2:3], v[2:3], v[26:27], v[22:23]
	v_pk_add_f32 v[22:23], v[28:29], 1.0 op_sel_hi:[1,0]
	v_cvt_pk_bf16_f32 v2, v2, v3
	v_pk_fma_f32 v[4:5], v[4:5], v[22:23], v[24:25]
	s_nop 0
	v_cvt_pk_bf16_f32 v3, v4, v5
	v_add_co_u32_e32 v4, vcc, 0x50cc000, v14
	s_nop 1
	v_addc_co_u32_e32 v5, vcc, 0, v15, vcc
	global_store_dwordx2 v[4:5], v[2:3], off offset:768
.LBB0_908:
	s_waitcnt vmcnt(4)
	v_mov_b64_e32 v[2:3], v[98:99]
	v_mov_b64_e32 v[4:5], v[100:101]
	s_nop 0
	v_mov_b64_e32 v[22:23], v[114:115]
	v_mov_b64_e32 v[24:25], v[116:117]
	v_pk_mul_f32 v[12:13], v[12:13], v[16:17]
	v_pk_mul_f32 v[10:11], v[10:11], v[16:17]
	s_and_b64 vcc, exec, s[4:5]
	s_mov_b64 s[2:3], -1
	v_pk_fma_f32 v[2:3], v[12:13], v[2:3], v[22:23]
	v_pk_fma_f32 v[4:5], v[10:11], v[4:5], v[24:25]
	s_cbranch_vccnz .LBB0_910
	v_lshl_add_u64 v[10:11], v[58:59], 0, v[0:1]
	s_mov_b64 s[2:3], 0
	global_store_dwordx4 v[10:11], v[2:5], off offset:2048
.LBB0_910:
	s_andn2_b64 vcc, exec, s[2:3]
	s_cbranch_vccnz .LBB0_912
	v_lshlrev_b32_e32 v12, 2, v40
	v_mov_b32_e32 v13, v1
	v_lshl_add_u64 v[10:11], v[20:21], 0, v[0:1]
	v_lshl_add_u64 v[22:23], v[18:19], 0, v[12:13]
	s_waitcnt vmcnt(4)
	v_mov_b64_e32 v[10:11], v[130:131]
	v_mov_b64_e32 v[12:13], v[132:133]
	s_nop 0
	v_mov_b64_e32 v[22:23], v[146:147]
	v_mov_b64_e32 v[24:25], v[148:149]
	v_pk_add_f32 v[22:23], v[22:23], 1.0 op_sel_hi:[1,0]
	s_nop 0
	v_pk_fma_f32 v[2:3], v[2:3], v[22:23], v[10:11]
	v_pk_add_f32 v[10:11], v[24:25], 1.0 op_sel_hi:[1,0]
	v_cvt_pk_bf16_f32 v2, v2, v3
	v_pk_fma_f32 v[4:5], v[4:5], v[10:11], v[12:13]
	s_nop 0
	v_cvt_pk_bf16_f32 v3, v4, v5
	v_add_co_u32_e32 v4, vcc, 0x50cc000, v14
	s_nop 1
	v_addc_co_u32_e32 v5, vcc, 0, v15, vcc
	global_store_dwordx2 v[4:5], v[2:3], off offset:1280
.LBB0_912:
	s_waitcnt vmcnt(3)
	v_mov_b64_e32 v[2:3], v[102:103]
	v_mov_b64_e32 v[4:5], v[104:105]
	s_nop 0
	v_mov_b64_e32 v[10:11], v[118:119]
	v_mov_b64_e32 v[12:13], v[120:121]
	v_pk_mul_f32 v[8:9], v[8:9], v[16:17]
	v_pk_mul_f32 v[6:7], v[6:7], v[16:17]
	s_and_b64 vcc, exec, s[4:5]
	s_mov_b64 s[2:3], -1
	v_pk_fma_f32 v[2:3], v[8:9], v[2:3], v[10:11]
	v_pk_fma_f32 v[4:5], v[6:7], v[4:5], v[12:13]
	s_cbranch_vccnz .LBB0_914
	v_lshl_add_u64 v[6:7], v[58:59], 0, v[0:1]
	s_mov_b64 s[2:3], 0
	global_store_dwordx4 v[6:7], v[2:5], off offset:3072
.LBB0_914:
	s_andn2_b64 vcc, exec, s[2:3]
	s_cbranch_vccnz .LBB0_870
	v_lshl_add_u64 v[6:7], v[20:21], 0, v[0:1]
	v_lshlrev_b32_e32 v0, 2, v42
	v_lshl_add_u64 v[10:11], v[18:19], 0, v[0:1]
	s_waitcnt vmcnt(3)
	v_mov_b64_e32 v[6:7], v[134:135]
	v_mov_b64_e32 v[8:9], v[136:137]
	s_nop 0
	v_mov_b64_e32 v[10:11], v[150:151]
	v_mov_b64_e32 v[12:13], v[152:153]
	v_pk_add_f32 v[10:11], v[10:11], 1.0 op_sel_hi:[1,0]
	s_nop 0
	v_pk_fma_f32 v[2:3], v[2:3], v[10:11], v[6:7]
	v_pk_add_f32 v[6:7], v[12:13], 1.0 op_sel_hi:[1,0]
	v_cvt_pk_bf16_f32 v2, v2, v3
	v_pk_fma_f32 v[4:5], v[4:5], v[6:7], v[8:9]
	s_nop 0
	v_cvt_pk_bf16_f32 v3, v4, v5
	v_add_co_u32_e32 v4, vcc, 0x50cc000, v14
	s_nop 1
	v_addc_co_u32_e32 v5, vcc, 0, v15, vcc
	global_store_dwordx2 v[4:5], v[2:3], off offset:1792
	s_branch .LBB0_870
